# HGRN chunk loop: lean prep (native log, in-place DPP scan), v_rsq for post norm, 2-deep input prefetch with counted vmcnt, gate loads off critical path
# speedup vs baseline: 1.0197x; 1.0197x over previous
; #define LAS __attribute__((address_space(3)))
; __device__ __forceinline__ float bf2f(bf16_t v) { return __uint_as_float(((unsigned)v) << 16); }
; __device__ __forceinline__ bf16_t f2bf(float f) { return (bf16_t)(pk2(f, 0.f) & 0xffffu); }
; __device__ __forceinline__ float wave_sum_fast(float x) { x = reduce16(x); return (rl_(x, 0) + rl_(x, 16)) + (rl_(x, 32) + rl_(x, 48)); }
; __device__ __forceinline__ void hgrn_post(const Ctx& F, const LAS unsigned char* Lp, bf16_t* Y, int b, int h, int c, int w, int lane, float gn0, float gn1, const bf16_t (&gq)[4][2]) {
; #pragma unroll
;     for (int i = 0; i < 4; ++i) {
;         const int tl = w + 8 * i; const size_t row = (size_t)b * S + 32 * c + tl;
;         const float oa = *(const LAS float*)(Lp + H_O + tl * HOP + 4 * lane), ob = *(const LAS float*)(Lp + H_O + tl * HOP + 4 * (64 + lane));
;         const float rstd = 1.0f / sqrtf(wave_sum_fast(oa * oa + ob * ob) * (1.0f / 128.f) + 1e-6f);
;         Y[row * D + h * 128 + lane] = f2bf(oa * rstd * gn0 * bf2f(gq[i][0]));
;         Y[row * D + h * 128 + 64 + lane] = f2bf(ob * rstd * gn1 * bf2f(gq[i][1]));
;     }
; }
.LBB0_1376:
	s_waitcnt vmcnt(0)
	s_or_b32 s6, s60, 0x7e0
	s_add_u32 s4, s6, s50
	s_addc_u32 s5, s61, 0
	s_lshl_b64 s[4:5], s[4:5], 11
	s_add_u32 s12, s62, s4
	s_addc_u32 s13, s63, s5
	s_add_u32 s4, s6, s48
	s_addc_u32 s5, s61, 0
	s_lshl_b64 s[4:5], s[4:5], 11
	s_add_u32 s10, s62, s4
	s_addc_u32 s11, s63, s5
	s_add_u32 s4, s6, s49
	s_addc_u32 s5, s61, 0
	s_lshl_b64 s[4:5], s[4:5], 11
	s_add_u32 s8, s62, s4
	s_addc_u32 s9, s63, s5
	s_add_u32 s4, s6, s54
	s_addc_u32 s5, s61, 0
	s_lshl_b64 s[4:5], s[4:5], 11
	s_add_u32 s6, s62, s4
	s_addc_u32 s7, s63, s5
	s_add_i32 s4, s43, 0
	v_add_u32_e32 v0, s4, v116
	v_add_u32_e32 v4, 0x18200, v0
	s_waitcnt lgkmcnt(0)
	s_barrier
	ds_read2st64_b32 v[0:1], v4 offset1:1
	ds_read2st64_b32 v[2:3], v4 offset0:33 offset1:34
	v_and_b32_e32 v5, 0xffff, v146
	v_lshlrev_b32_e32 v5, 16, v5
	v_and_b32_e32 v10, 0xffff, v147
	s_waitcnt lgkmcnt(1)
	v_mul_f32_e32 v6, v1, v1
	v_fmac_f32_e32 v6, v0, v0
	v_lshlrev_b32_e32 v10, 16, v10
	v_and_b32_e32 v11, 0xffff, v143
	v_add_f32_dpp v6, v6, v6 quad_perm:[1,0,3,2] row_mask:0xf bank_mask:0xf bound_ctrl:1
	v_and_b32_e32 v12, 0xffff, v144
	v_and_b32_e32 v13, 0xffff, v145
	v_add_f32_dpp v6, v6, v6 quad_perm:[2,3,0,1] row_mask:0xf bank_mask:0xf bound_ctrl:1
	v_and_b32_e32 v14, 0xffff, v140
	v_and_b32_e32 v15, 0xffff, v141
	v_add_f32_dpp v6, v6, v6 row_half_mirror row_mask:0xf bank_mask:0xf bound_ctrl:1
	v_and_b32_e32 v16, 0xffff, v142
	s_add_i32 s79, s79, s90
	v_add_f32_dpp v6, v6, v6 row_mirror row_mask:0xf bank_mask:0xf bound_ctrl:1
	s_add_i32 s69, s69, s70
	v_readlane_b32 s5, v6, 16
	v_readlane_b32 s4, v6, 0
	s_cmpk_gt_i32 s79, 0xff
	v_mov_b32_e32 v7, s5
	v_readlane_b32 s5, v6, 48
	v_add_f32_e32 v7, s4, v7
	v_readlane_b32 s4, v6, 32
	v_mov_b32_e32 v6, s5
	s_nop 0
	v_add_f32_e32 v6, s4, v6
	v_add_f32_e32 v6, v7, v6
	v_fmamk_f32 v6, v6, 0x3c000000, v110
	v_rsq_f32_e32 v17, v6
	s_nop 0
	v_mul_f32_e32 v0, v0, v17
	v_mul_f32_e32 v0, v115, v0
	v_add_u32_e32 v8, 0x80, v4
	v_mul_f32_e32 v0, v0, v5
	ds_read2st64_b32 v[4:5], v8 offset0:16 offset1:17
	v_cvt_pk_bf16_f32 v0, v0, s0
	v_lshl_add_u64 v[6:7], s[12:13], 0, v[100:101]
	global_store_short v[6:7], v0, off
	v_mul_f32_e32 v1, v1, v17
	s_waitcnt lgkmcnt(0)
	v_mul_f32_e32 v0, v5, v5
	v_fmac_f32_e32 v0, v4, v4
	v_mul_f32_e32 v1, v114, v1
	v_mul_f32_e32 v1, v1, v10
	v_add_f32_dpp v0, v0, v0 quad_perm:[1,0,3,2] row_mask:0xf bank_mask:0xf bound_ctrl:1
	v_cvt_pk_bf16_f32 v1, v1, s0
	global_store_short v[6:7], v1, off offset:128
	v_add_f32_dpp v0, v0, v0 quad_perm:[2,3,0,1] row_mask:0xf bank_mask:0xf bound_ctrl:1
	ds_read2st64_b32 v[8:9], v8 offset0:49 offset1:50
	s_nop 0
	v_add_f32_dpp v0, v0, v0 row_half_mirror row_mask:0xf bank_mask:0xf bound_ctrl:1
	s_nop 1
	v_add_f32_dpp v0, v0, v0 row_mirror row_mask:0xf bank_mask:0xf bound_ctrl:1
	s_nop 0
	v_readlane_b32 s5, v0, 16
	v_readlane_b32 s4, v0, 0
	s_nop 0
	v_mov_b32_e32 v18, s5
	v_readlane_b32 s5, v0, 48
	v_add_f32_e32 v18, s4, v18
	v_readlane_b32 s4, v0, 32
	v_mov_b32_e32 v0, s5
	s_nop 0
	v_add_f32_e32 v0, s4, v0
	v_add_f32_e32 v0, v18, v0
	v_fmamk_f32 v0, v0, 0x3c000000, v110
	v_rsq_f32_e32 v6, v0
	s_nop 0
	v_mul_f32_e32 v0, v4, v6
	v_mul_f32_e32 v0, v115, v0
	v_lshlrev_b32_e32 v1, 16, v11
	v_mul_f32_e32 v0, v0, v1
	v_cvt_pk_bf16_f32 v4, v0, s0
	v_lshl_add_u64 v[0:1], s[10:11], 0, v[100:101]
	global_store_short v[0:1], v4, off
	v_mul_f32_e32 v4, v3, v3
	v_fmac_f32_e32 v4, v2, v2
	v_mul_f32_e32 v5, v5, v6
	v_mul_f32_e32 v5, v114, v5
	v_add_f32_dpp v4, v4, v4 quad_perm:[1,0,3,2] row_mask:0xf bank_mask:0xf bound_ctrl:1
	v_lshlrev_b32_e32 v6, 16, v12
	v_mul_f32_e32 v5, v5, v6
	v_add_f32_dpp v4, v4, v4 quad_perm:[2,3,0,1] row_mask:0xf bank_mask:0xf bound_ctrl:1
	v_cvt_pk_bf16_f32 v5, v5, s0
	global_store_short v[0:1], v5, off offset:128
	v_add_f32_dpp v4, v4, v4 row_half_mirror row_mask:0xf bank_mask:0xf bound_ctrl:1
	s_nop 1
	v_add_f32_dpp v4, v4, v4 row_mirror row_mask:0xf bank_mask:0xf bound_ctrl:1
	s_nop 0
	v_readlane_b32 s5, v4, 16
	v_readlane_b32 s4, v4, 0
	s_nop 0
	v_mov_b32_e32 v7, s5
	v_readlane_b32 s5, v4, 48
	v_add_f32_e32 v7, s4, v7
	v_readlane_b32 s4, v4, 32
	v_mov_b32_e32 v4, s5
	s_nop 0
	v_add_f32_e32 v4, s4, v4
	v_add_f32_e32 v4, v7, v4
	v_fmamk_f32 v4, v4, 0x3c000000, v110
	v_rsq_f32_e32 v4, v4
	s_nop 0
	v_mul_f32_e32 v0, v2, v4
	v_mul_f32_e32 v0, v115, v0
	v_lshlrev_b32_e32 v1, 16, v13
	v_mul_f32_e32 v0, v0, v1
	v_cvt_pk_bf16_f32 v2, v0, s0
	v_lshl_add_u64 v[0:1], s[8:9], 0, v[100:101]
	global_store_short v[0:1], v2, off
	s_waitcnt lgkmcnt(0)
	v_mul_f32_e32 v2, v9, v9
	v_fmac_f32_e32 v2, v8, v8
	v_mul_f32_e32 v3, v3, v4
	v_mul_f32_e32 v3, v114, v3
	v_add_f32_dpp v2, v2, v2 quad_perm:[1,0,3,2] row_mask:0xf bank_mask:0xf bound_ctrl:1
	v_lshlrev_b32_e32 v4, 16, v14
	v_mul_f32_e32 v3, v3, v4
	v_add_f32_dpp v2, v2, v2 quad_perm:[2,3,0,1] row_mask:0xf bank_mask:0xf bound_ctrl:1
	v_cvt_pk_bf16_f32 v3, v3, s0
	global_store_short v[0:1], v3, off offset:128
	v_add_f32_dpp v2, v2, v2 row_half_mirror row_mask:0xf bank_mask:0xf bound_ctrl:1
	s_nop 1
	v_add_f32_dpp v2, v2, v2 row_mirror row_mask:0xf bank_mask:0xf bound_ctrl:1
	s_nop 0
	v_readlane_b32 s5, v2, 16
	v_readlane_b32 s4, v2, 0
	s_nop 0
	v_mov_b32_e32 v5, s5
	v_readlane_b32 s5, v2, 48
	v_add_f32_e32 v5, s4, v5
	v_readlane_b32 s4, v2, 32
	v_mov_b32_e32 v2, s5
	s_nop 0
	v_add_f32_e32 v2, s4, v2
	v_add_f32_e32 v2, v5, v2
	v_fmamk_f32 v2, v2, 0x3c000000, v110
	v_rsq_f32_e32 v2, v2
	s_nop 0
	v_mul_f32_e32 v0, v8, v2
	v_mul_f32_e32 v0, v115, v0
	v_lshlrev_b32_e32 v1, 16, v15
	v_mul_f32_e32 v0, v0, v1
	v_cvt_pk_bf16_f32 v3, v0, s0
	v_lshl_add_u64 v[0:1], s[6:7], 0, v[100:101]
	v_mul_f32_e32 v2, v9, v2
	global_store_short v[0:1], v3, off
	v_mul_f32_e32 v2, v114, v2
	v_lshlrev_b32_e32 v3, 16, v16
	v_mul_f32_e32 v2, v2, v3
	v_cvt_pk_bf16_f32 v2, v2, s0
	global_store_short v[0:1], v2, off offset:128
	s_barrier
	s_cbranch_scc1 .LBB0_1403
; __device__ __forceinline__ int lane_id_() { int l; asm volatile("v_mbcnt_lo_u32_b32 %0, -1, 0\n\tv_mbcnt_hi_u32_b32 %0, -1, %0" : "=v"(l)); return l; }
; __device__ __forceinline__ void hgrn_chunked_bh(const Ctx& F, int b, int h) {
;     ...
;     const int lane = lane_id_(), w = F.wid, tid = w * 64 + lane, c16 = lane & 15, g = lane >> 4;
;     const int pt = lane & 31, phalf = lane >> 5, k0 = 16 * w + 8 * phalf;
;     float lb8[8];
;     { const f32x4 l0 = *(const f32x4*)(lb + h * 128 + k0), l1 = *(const f32x4*)(lb + h * 128 + k0 + 4); lb8[0] = l0[0]; lb8[1] = l0[1]; lb8[2] = l0[2]; lb8[3] = l0[3]; lb8[4] = l1[0]; lb8[5] = l1[1]; lb8[6] = l1[2]; lb8[7] = l1[3]; }
;     const float gn0 = F_hg_norm[lane], gn1 = F_hg_norm[64 + lane];
;     f32x4 st[8];
; #pragma unroll
;     for (int i = 0; i < 8; ++i) st[i] = (f32x4){0.f, 0.f, 0.f, 0.f};
;     u32x4 rq, rf, rv;
;     { const bf16_t* p = proj + ((size_t)b * S + pt) * IN_ODD + h * 128 + k0; rq = *(const u32x4*)p; rf = *(const u32x4*)(p + 1024); rv = *(const u32x4*)(p + 2048); }
;     bf16_t gqp[4][2] = {};
;     ...
;         if (c + 1 < S / 32) { const bf16_t* p = proj + ((size_t)b * S + 32 * (c + 1) + pt) * IN_ODD + h * 128 + k0; rq = *(const u32x4*)p; rf = *(const u32x4*)(p + 1024); rv = *(const u32x4*)(p + 2048); }
;         bf16_t gq[4][2];
; #pragma unroll
;         for (int i = 0; i < 4; ++i) { const bf16_t* gp = proj + ((size_t)b * S + 32 * c + w + 8 * i) * IN_ODD + 3072 + h * 128; gq[i][0] = gp[lane]; gq[i][1] = gp[64 + lane]; }
.LBB0_1377:
	s_lshl_b32 s4, s69, 1
	s_and_b32 s42, s4, 0x700
	s_lshl_b32 s4, s79, 7
	s_and_b32 s18, s4, 0x380
	v_mbcnt_lo_u32_b32 v20, -1, 0
	v_mbcnt_hi_u32_b32 v20, -1, v20
	v_and_b32_e32 v172, 15, v20
	v_and_b32_e32 v173, 16, v20
	v_lshl_add_u32 v172, s50, 4, v172
	v_lshlrev_b32_e32 v172, 2, v172
	v_lshl_add_u32 v172, v173, 5, v172
	s_ashr_i32 s40, s79, 3
	s_waitcnt lgkmcnt(0)
	v_ashrrev_i32_e32 v0, 2, v20
	s_lshl_b32 s4, s18, 2
	v_and_b32_e32 v22, -8, v0
	s_add_u32 s4, s0, s4
	v_add_u32_e32 v102, s3, v22
	s_addc_u32 s5, s1, 0
	v_ashrrev_i32_e32 v103, 31, v102
	v_lshl_add_u64 v[8:9], v[102:103], 2, s[4:5]
	global_load_dwordx4 v[0:3], v[8:9], off
	global_load_dwordx4 v[4:7], v[8:9], off offset:16
	s_load_dwordx2 s[16:17], s[56:57], 0xd0
	v_ashrrev_i32_e32 v8, 4, v20
	v_and_b32_e32 v23, 15, v20
	v_ashrrev_i32_e32 v21, 31, v20
	v_lshlrev_b32_e32 v120, 3, v8
	v_lshlrev_b32_e32 v25, 2, v8
	v_or_b32_e32 v8, s3, v23
	s_ashr_i32 s41, s40, 31
	v_and_b32_e32 v24, 31, v20
	v_mul_lo_u32 v122, v8, s72
	s_lshl_b32 s52, s18, 1
	s_lshl_b64 s[60:61], s[40:41], 11
	s_waitcnt lgkmcnt(0)
	v_lshl_add_u64 v[8:9], v[20:21], 2, s[16:17]
	v_readlane_b32 s16, v254, 4
	v_readlane_b32 s17, v254, 5
	s_add_u32 s16, s16, s52
	flat_load_dword v115, v[8:9]
	flat_load_dword v114, v[8:9] offset:256
	v_or_b32_e32 v8, s60, v24
	v_mov_b32_e32 v9, s61
	s_addc_u32 s17, s17, 0
	v_lshlrev_b64 v[8:9], 13, v[8:9]
	v_lshl_add_u64 v[8:9], s[16:17], 0, v[8:9]
	v_lshl_add_u64 v[16:17], v[102:103], 1, v[8:9]
	v_add_co_u32_e32 v188, vcc, 0x40000, v16
	s_nop 1
	v_addc_co_u32_e32 v189, vcc, 0, v17, vcc
	v_add_co_u32_e32 v190, vcc, 0x41000, v16
	s_nop 1
	v_addc_co_u32_e32 v191, vcc, 0, v17, vcc
	global_load_dwordx4 v[176:179], v[188:189], off
	global_load_dwordx4 v[180:183], v[188:189], off offset:2048
	global_load_dwordx4 v[184:187], v[190:191], off
	global_load_dwordx4 v[8:11], v[16:17], off
	global_load_dwordx4 v[12:15], v[16:17], off offset:2048
	v_add_co_u32_e32 v16, vcc, s71, v16
	v_readlane_b32 s53, v254, 0
	s_nop 0
	v_addc_co_u32_e32 v17, vcc, 0, v17, vcc
	global_load_dwordx4 v[16:19], v[16:17], off
	s_add_u32 s62, s53, s52
	v_readlane_b32 s52, v254, 1
	v_or_b32_e32 v26, 16, v23
	s_addc_u32 s63, s52, 0
	s_lshl_b64 s[40:41], s[40:41], 24
	v_add_u32_e32 v27, 16, v25
	v_cmp_gt_i32_e64 s[8:9], v25, v23
	v_cmp_lt_i32_e64 s[10:11], v25, v23
	v_or_b32_e32 v28, 2, v25
	v_or_b32_e32 v29, 3, v25
	v_cmp_gt_i32_e64 s[12:13], v25, v26
	v_cmp_lt_i32_e64 s[14:15], v25, v26
	v_add_u32_e32 v30, 17, v25
	v_add_u32_e32 v31, 18, v25
	v_add_u32_e32 v25, 19, v25
	s_or_b32 s40, s40, s42
	v_and_b32_e32 v117, -16, v20
	v_lshlrev_b32_e32 v116, 2, v20
	v_mul_u32_u24_e32 v121, 0x110, v23
	v_cmp_gt_i32_e64 s[16:17], v28, v23
	v_cmp_gt_i32_e64 s[18:19], v29, v23
	v_cmp_gt_i32_e64 s[24:25], v27, v23
	v_cmp_gt_i32_e64 s[26:27], v30, v23
	v_cmp_gt_i32_e64 s[28:29], v31, v23
	v_cmp_gt_i32_e64 s[30:31], v25, v23
	v_mul_u32_u24_e32 v133, 0x50, v23
	v_mul_u32_u24_e32 v134, 0x210, v23
	s_waitcnt vmcnt(0)
	v_lshlrev_b64 v[100:101], 1, v[20:21]
	v_lshl_or_b32 v20, v24, 13, s40
	v_mov_b32_e32 v21, s41
	v_ashrrev_i32_e32 v23, 31, v22
	s_add_u32 s64, s55, s40
	v_lshl_add_u64 v[20:21], v[22:23], 1, v[20:21]
	s_addc_u32 s65, s68, s41
	v_lshl_add_u64 v[108:109], s[58:59], 0, v[20:21]
	v_mov_b32_e32 v20, 0
	v_cmp_eq_u32_e64 s[4:5], 15, v24
	v_cmp_eq_u32_e64 s[6:7], 31, v24
	v_mul_u32_u24_e32 v118, 0x110, v24
	v_lshlrev_b32_e32 v119, 1, v24
	v_lshlrev_b32_e32 v103, 1, v102
	v_mul_lo_u32 v123, v102, s72
	v_cmp_gt_i32_e64 s[20:21], v28, v26
	v_cmp_gt_i32_e64 s[22:23], v29, v26
	v_cmp_gt_i32_e64 s[34:35], v30, v26
	v_cmp_gt_i32_e64 s[36:37], v31, v26
	v_cmp_gt_i32_e64 s[38:39], v25, v26
	v_lshlrev_b32_e32 v124, 2, v27
	v_sub_f32_e32 v125, 1.0, v0
	v_sub_f32_e32 v126, 1.0, v1
	v_sub_f32_e32 v127, 1.0, v2
	v_sub_f32_e32 v128, 1.0, v3
	v_sub_f32_e32 v129, 1.0, v4
	v_sub_f32_e32 v130, 1.0, v5
	v_sub_f32_e32 v131, 1.0, v6
	v_sub_f32_e32 v132, 1.0, v7
	v_add_u32_e32 v135, 0, v116
	v_lshl_add_u64 v[104:105], s[62:63], 0, v[100:101]
	v_lshl_add_u64 v[106:107], s[64:65], 0, v[100:101]
	s_movk_i32 s42, 0xffe0
	s_mov_b64 s[64:65], 0
	s_mov_b32 s66, -1
	v_mov_b32_e32 v21, v20
	v_mov_b32_e32 v22, v20
	v_mov_b32_e32 v23, v20
	v_mov_b32_e32 v24, v20
	v_mov_b32_e32 v25, v20
	v_mov_b32_e32 v26, v20
	v_mov_b32_e32 v27, v20
	v_mov_b32_e32 v28, v20
	v_mov_b32_e32 v29, v20
	v_mov_b32_e32 v30, v20
	v_mov_b32_e32 v31, v20
	v_mov_b32_e32 v32, v20
	v_mov_b32_e32 v33, v20
	v_mov_b32_e32 v34, v20
	v_mov_b32_e32 v35, v20
	v_mov_b32_e32 v36, v20
	v_mov_b32_e32 v37, v20
	v_mov_b32_e32 v38, v20
	v_mov_b32_e32 v39, v20
	v_mov_b32_e32 v40, v20
	v_mov_b32_e32 v41, v20
	v_mov_b32_e32 v42, v20
	v_mov_b32_e32 v43, v20
	v_mov_b32_e32 v44, v20
	v_mov_b32_e32 v45, v20
	v_mov_b32_e32 v46, v20
	v_mov_b32_e32 v47, v20
	v_mov_b32_e32 v48, v20
	v_mov_b32_e32 v49, v20
	v_mov_b32_e32 v50, v20
	v_mov_b32_e32 v51, v20
	v_mov_b32_e32 v139, 0
	v_mov_b32_e32 v138, 0
	v_mov_b32_e32 v137, 0
	v_mov_b32_e32 v136, 0
	s_branch .LBB0_1379
.LBB0_1378:
	v_lshl_add_u64 v[52:53], v[106:107], 0, s[64:65]
	v_add_co_u32_e32 v54, vcc, 0xc201000, v52
	s_nop 1
	v_addc_co_u32_e32 v55, vcc, 0, v53, vcc
	v_add_co_u32_e32 v56, vcc, 0xc211000, v52
	s_nop 1
	v_addc_co_u32_e32 v57, vcc, 0, v53, vcc
	v_add_co_u32_e32 v58, vcc, 0xc221000, v52
	s_nop 1
	v_addc_co_u32_e32 v59, vcc, 0, v53, vcc
	v_add_co_u32_e32 v52, vcc, 0xc231000, v52
	s_nop 1
	v_addc_co_u32_e32 v53, vcc, 0, v53, vcc
	global_load_ushort v146, v[54:55], off offset:2048
	global_load_ushort v147, v[54:55], off offset:2176
	global_load_ushort v143, v[56:57], off offset:2048
	global_load_ushort v144, v[56:57], off offset:2176
	global_load_ushort v145, v[58:59], off offset:2048
	global_load_ushort v140, v[58:59], off offset:2176
	global_load_ushort v141, v[52:53], off offset:2048
	global_load_ushort v142, v[52:53], off offset:2176
	s_add_i32 s42, s42, 32
	s_add_u32 s64, s64, 0x40000
	s_addc_u32 s65, s65, 0
	s_cmp_lg_u32 s64, 0x1000000
	s_mov_b32 s66, s80
	s_cbranch_scc0 .LBB0_1376
; #define LAS __attribute__((address_space(3)))
; __device__ __forceinline__ float sigmoidf_(float x) { return __builtin_amdgcn_rcpf(1.f + __expf(-x)); }
; __device__ __forceinline__ void hgrn_chunked_bh(const Ctx& F, int b, int h) {
;     ...
;             float q[8], fv[8], Bv[8], kk[8];
;             unpack8(rq, q); unpack8(rf, fv);
; #pragma unroll
;             for (int e = 0; e < 8; ++e) {
;                 const float f = lb8[e] + (1.0f - lb8[e]) * sigmoidf_(fv[e]); kk[e] = 1.0f - f;
;                 float x = __logf(f);
;                 x += __int_as_float(__builtin_amdgcn_update_dpp(0, __float_as_int(x), 0x111, 0xf, 0xf, false));
;                 x += __int_as_float(__builtin_amdgcn_update_dpp(0, __float_as_int(x), 0x112, 0xf, 0xf, false));
;                 x += __int_as_float(__builtin_amdgcn_update_dpp(0, __float_as_int(x), 0x114, 0xf, 0xf, false));
;                 x += __int_as_float(__builtin_amdgcn_update_dpp(0, __float_as_int(x), 0x118, 0xf, 0xf, false));
;                 x += __int_as_float(__builtin_amdgcn_update_dpp(0, __float_as_int(x), 0x142, 0xa, 0xf, false));
;                 Bv[e] = x;
;             }
;             LAS float* PW = (LAS float*)(Ls + H_PART);
;             if (pt == 15) { *(LAS f32x4*)(PW + k0) = (f32x4){Bv[0], Bv[1], Bv[2], Bv[3]}; *(LAS f32x4*)(PW + k0 + 4) = (f32x4){Bv[4], Bv[5], Bv[6], Bv[7]}; }
;             if (pt == 31) { *(LAS f32x4*)(PW + 128 + k0) = (f32x4){Bv[0], Bv[1], Bv[2], Bv[3]}; *(LAS f32x4*)(PW + 128 + k0 + 4) = (f32x4){Bv[4], Bv[5], Bv[6], Bv[7]}; }
;             asm volatile("s_waitcnt lgkmcnt(0)" ::: "memory");
;             const f32x4 m0 = *(const LAS f32x4*)(PW + k0), m1 = *(const LAS f32x4*)(PW + k0 + 4), e0 = *(const LAS f32x4*)(PW + 128 + k0), e1 = *(const LAS f32x4*)(PW + 128 + k0 + 4);
;             float qm[8], km[8], kd[8];
; #pragma unroll
;             for (int e = 0; e < 8; ++e) { const float bmid = e < 4 ? m0[e & 3] : m1[e & 3], blast = e < 4 ? e0[e & 3] : e1[e & 3];
;                 const float ex = __expf(fminf(fmaxf(Bv[e] - bmid, -60.f), 60.f));
;                 qm[e] = q[e] * ex; km[e] = kk[e] * __builtin_amdgcn_rcpf(ex); kd[e] = km[e] * __expf(blast - bmid);
;                 if (pt == 31) { ((LAS float*)(Ls + H_EM))[k0 + e] = __expf(bmid); ((LAS float*)(Ls + H_EL))[k0 + e] = __expf(blast); } }
.LBB0_1379:
	s_add_i32 s80, s66, 1
	s_bitcmp1_b32 s80, 0
	s_cselect_b32 s67, 0xe200, 0
	v_lshlrev_b32_e32 v52, 16, v12
	v_and_b32_e32 v53, 0xffff0000, v12
	v_lshlrev_b32_e32 v54, 16, v13
	v_and_b32_e32 v55, 0xffff0000, v13
	v_lshlrev_b32_e32 v56, 16, v14
	v_and_b32_e32 v57, 0xffff0000, v14
	v_lshlrev_b32_e32 v58, 16, v15
	v_and_b32_e32 v59, 0xffff0000, v15
	v_mul_f32_e32 v52, 0xbfb8aa3b, v52
	v_mul_f32_e32 v53, 0xbfb8aa3b, v53
	v_mul_f32_e32 v54, 0xbfb8aa3b, v54
	v_mul_f32_e32 v55, 0xbfb8aa3b, v55
	v_mul_f32_e32 v56, 0xbfb8aa3b, v56
	v_mul_f32_e32 v57, 0xbfb8aa3b, v57
	v_mul_f32_e32 v58, 0xbfb8aa3b, v58
	v_mul_f32_e32 v59, 0xbfb8aa3b, v59
	v_exp_f32_e32 v52, v52
	v_exp_f32_e32 v53, v53
	v_exp_f32_e32 v54, v54
	v_exp_f32_e32 v55, v55
	v_exp_f32_e32 v56, v56
	v_exp_f32_e32 v57, v57
	v_exp_f32_e32 v58, v58
	v_exp_f32_e32 v59, v59
	v_add_f32_e32 v52, 1.0, v52
	v_add_f32_e32 v53, 1.0, v53
	v_add_f32_e32 v54, 1.0, v54
	v_add_f32_e32 v55, 1.0, v55
	v_add_f32_e32 v56, 1.0, v56
	v_add_f32_e32 v57, 1.0, v57
	v_add_f32_e32 v58, 1.0, v58
	v_add_f32_e32 v59, 1.0, v59
	v_rcp_f32_e32 v52, v52
	v_rcp_f32_e32 v53, v53
	v_rcp_f32_e32 v54, v54
	v_rcp_f32_e32 v55, v55
	v_rcp_f32_e32 v56, v56
	v_rcp_f32_e32 v57, v57
	v_rcp_f32_e32 v58, v58
	v_rcp_f32_e32 v59, v59
	v_lshl_add_u32 v84, v102, 2, s67
	v_fma_f32 v76, v125, v52, v0
	v_fma_f32 v77, v126, v53, v1
	v_fma_f32 v78, v127, v54, v2
	v_fma_f32 v79, v128, v55, v3
	v_fma_f32 v80, v129, v56, v4
	v_fma_f32 v81, v130, v57, v5
	v_fma_f32 v82, v131, v58, v6
	v_fma_f32 v83, v132, v59, v7
	v_log_f32_e32 v52, v76
	v_log_f32_e32 v53, v77
	v_log_f32_e32 v54, v78
	v_log_f32_e32 v55, v79
	v_log_f32_e32 v56, v80
	v_log_f32_e32 v57, v81
	v_log_f32_e32 v58, v82
	v_log_f32_e32 v59, v83
	v_mul_f32_e32 v52, 0x3f317217, v52
	v_mul_f32_e32 v53, 0x3f317217, v53
	v_mul_f32_e32 v54, 0x3f317217, v54
	v_mul_f32_e32 v55, 0x3f317217, v55
	v_mul_f32_e32 v56, 0x3f317217, v56
	v_mul_f32_e32 v57, 0x3f317217, v57
	v_mul_f32_e32 v58, 0x3f317217, v58
	v_mul_f32_e32 v59, 0x3f317217, v59
	v_add_f32_dpp v52, v52, v52 row_shr:1 row_mask:0xf bank_mask:0xf bound_ctrl:1
	v_add_f32_dpp v53, v53, v53 row_shr:1 row_mask:0xf bank_mask:0xf bound_ctrl:1
	v_add_f32_dpp v54, v54, v54 row_shr:1 row_mask:0xf bank_mask:0xf bound_ctrl:1
	v_add_f32_dpp v55, v55, v55 row_shr:1 row_mask:0xf bank_mask:0xf bound_ctrl:1
	v_add_f32_dpp v56, v56, v56 row_shr:1 row_mask:0xf bank_mask:0xf bound_ctrl:1
	v_add_f32_dpp v57, v57, v57 row_shr:1 row_mask:0xf bank_mask:0xf bound_ctrl:1
	v_add_f32_dpp v58, v58, v58 row_shr:1 row_mask:0xf bank_mask:0xf bound_ctrl:1
	v_add_f32_dpp v59, v59, v59 row_shr:1 row_mask:0xf bank_mask:0xf bound_ctrl:1
	v_add_f32_dpp v52, v52, v52 row_shr:2 row_mask:0xf bank_mask:0xf bound_ctrl:1
	v_add_f32_dpp v53, v53, v53 row_shr:2 row_mask:0xf bank_mask:0xf bound_ctrl:1
	v_add_f32_dpp v54, v54, v54 row_shr:2 row_mask:0xf bank_mask:0xf bound_ctrl:1
	v_add_f32_dpp v55, v55, v55 row_shr:2 row_mask:0xf bank_mask:0xf bound_ctrl:1
	v_add_f32_dpp v56, v56, v56 row_shr:2 row_mask:0xf bank_mask:0xf bound_ctrl:1
	v_add_f32_dpp v57, v57, v57 row_shr:2 row_mask:0xf bank_mask:0xf bound_ctrl:1
	v_add_f32_dpp v58, v58, v58 row_shr:2 row_mask:0xf bank_mask:0xf bound_ctrl:1
	v_add_f32_dpp v59, v59, v59 row_shr:2 row_mask:0xf bank_mask:0xf bound_ctrl:1
	v_add_f32_dpp v52, v52, v52 row_shr:4 row_mask:0xf bank_mask:0xf bound_ctrl:1
	v_add_f32_dpp v53, v53, v53 row_shr:4 row_mask:0xf bank_mask:0xf bound_ctrl:1
	v_add_f32_dpp v54, v54, v54 row_shr:4 row_mask:0xf bank_mask:0xf bound_ctrl:1
	v_add_f32_dpp v55, v55, v55 row_shr:4 row_mask:0xf bank_mask:0xf bound_ctrl:1
	v_add_f32_dpp v56, v56, v56 row_shr:4 row_mask:0xf bank_mask:0xf bound_ctrl:1
	v_add_f32_dpp v57, v57, v57 row_shr:4 row_mask:0xf bank_mask:0xf bound_ctrl:1
	v_add_f32_dpp v58, v58, v58 row_shr:4 row_mask:0xf bank_mask:0xf bound_ctrl:1
	v_add_f32_dpp v59, v59, v59 row_shr:4 row_mask:0xf bank_mask:0xf bound_ctrl:1
	v_add_f32_dpp v52, v52, v52 row_shr:8 row_mask:0xf bank_mask:0xf bound_ctrl:1
	v_add_f32_dpp v53, v53, v53 row_shr:8 row_mask:0xf bank_mask:0xf bound_ctrl:1
	v_add_f32_dpp v54, v54, v54 row_shr:8 row_mask:0xf bank_mask:0xf bound_ctrl:1
	v_add_f32_dpp v55, v55, v55 row_shr:8 row_mask:0xf bank_mask:0xf bound_ctrl:1
	v_add_f32_dpp v56, v56, v56 row_shr:8 row_mask:0xf bank_mask:0xf bound_ctrl:1
	v_add_f32_dpp v57, v57, v57 row_shr:8 row_mask:0xf bank_mask:0xf bound_ctrl:1
	v_add_f32_dpp v58, v58, v58 row_shr:8 row_mask:0xf bank_mask:0xf bound_ctrl:1
	v_add_f32_dpp v59, v59, v59 row_shr:8 row_mask:0xf bank_mask:0xf bound_ctrl:1
	v_add_f32_dpp v52, v52, v52 row_bcast:15 row_mask:0xa bank_mask:0xf
	v_add_f32_dpp v53, v53, v53 row_bcast:15 row_mask:0xa bank_mask:0xf
	v_add_f32_dpp v54, v54, v54 row_bcast:15 row_mask:0xa bank_mask:0xf
	v_add_f32_dpp v55, v55, v55 row_bcast:15 row_mask:0xa bank_mask:0xf
	v_add_f32_dpp v56, v56, v56 row_bcast:15 row_mask:0xa bank_mask:0xf
	v_add_f32_dpp v57, v57, v57 row_bcast:15 row_mask:0xa bank_mask:0xf
	v_add_f32_dpp v58, v58, v58 row_bcast:15 row_mask:0xa bank_mask:0xf
	v_add_f32_dpp v59, v59, v59 row_bcast:15 row_mask:0xa bank_mask:0xf
	s_and_saveexec_b64 s[40:41], s[4:5]
	ds_write_b128 v84, v[52:55] offset:38912
	ds_write_b128 v84, v[56:59] offset:38928
	s_mov_b64 exec, s[6:7]
	ds_write_b128 v84, v[52:55] offset:39424
	ds_write_b128 v84, v[56:59] offset:39440
	s_mov_b64 exec, s[40:41]
	ds_read_b128 v[60:63], v84 offset:38912
	ds_read_b128 v[68:71], v84 offset:38928
	ds_read_b128 v[64:67], v84 offset:39424
	ds_read_b128 v[72:75], v84 offset:39440
	v_add_u32_e32 v173, s67, v172
	ds_read_b32 v174, v173 offset:38912
	s_waitcnt lgkmcnt(0)
; #define LAS __attribute__((address_space(3)))
; __device__ __forceinline__ unsigned pk2(float lo, float hi) { f32x2 v = {lo, hi}; bf16x2_t b = __builtin_convertvector(v, bf16x2_t); return __builtin_bit_cast(unsigned, b); }
; __device__ __forceinline__ bf16_t f2bf(float f) { return (bf16_t)(pk2(f, 0.f) & 0xffffu); }
; __device__ __forceinline__ void hgrn_chunked_bh(const Ctx& F, int b, int h) {
;     ...
;             for (int e = 0; e < 8; ++e) { const float bmid = e < 4 ? m0[e & 3] : m1[e & 3], blast = e < 4 ? e0[e & 3] : e1[e & 3];
;                 const float ex = __expf(fminf(fmaxf(Bv[e] - bmid, -60.f), 60.f));
;                 qm[e] = q[e] * ex; km[e] = kk[e] * __builtin_amdgcn_rcpf(ex); kd[e] = km[e] * __expf(blast - bmid);
;                 if (pt == 31) { ((LAS float*)(Ls + H_EM))[k0 + e] = __expf(bmid); ((LAS float*)(Ls + H_EL))[k0 + e] = __expf(blast); } }
;             *(LAS u32x4*)(Ls + H_QM + pt * HQP + 2 * k0) = (u32x4){pk2(qm[0], qm[1]), pk2(qm[2], qm[3]), pk2(qm[4], qm[5]), pk2(qm[6], qm[7])};
;             *(LAS u32x4*)(Ls + H_KM + pt * HQP + 2 * k0) = (u32x4){pk2(km[0], km[1]), pk2(km[2], km[3]), pk2(km[4], km[5]), pk2(km[6], km[7])};
; #pragma unroll
;             for (int e = 0; e < 8; ++e) { *(LAS bf16_t*)(Ls + H_KD + (k0 + e) * HTP + 2 * pt) = f2bf(kd[e]);
;                 const unsigned wv = rv[e >> 1]; *(LAS bf16_t*)(Ls + H_VT + (k0 + e) * HTP + 2 * pt) = (bf16_t)((e & 1) ? (wv >> 16) : (wv & 0xffffu)); }
;         }
;         if (c + 1 < S / 32) { const bf16_t* p = proj + ((size_t)b * S + 32 * (c + 1) + pt) * IN_ODD + h * 128 + k0; rq = *(const u32x4*)p; rf = *(const u32x4*)(p + 1024); rv = *(const u32x4*)(p + 2048); }
	v_mul_f32_e32 v174, 0x3fb8aa3b, v174
	v_exp_f32_e32 v174, v174
	s_nop 0
	ds_write_b32 v173, v174 offset:37888
	v_sub_f32_e32 v59, v59, v71
	v_med3_f32 v59, v59, s76, v113
	v_mul_f32_e32 v59, 0x3fb8aa3b, v59
	v_exp_f32_e32 v59, v59
	v_sub_f32_e32 v58, v58, v70
	v_med3_f32 v58, v58, s76, v113
	v_mul_f32_e32 v58, 0x3fb8aa3b, v58
	v_sub_f32_e32 v71, v75, v71
	v_rcp_f32_e32 v75, v59
	v_exp_f32_e32 v58, v58
	v_sub_f32_e32 v57, v57, v69
	v_sub_f32_e32 v56, v56, v68
	v_med3_f32 v57, v57, s76, v113
	v_med3_f32 v56, v56, s76, v113
	v_sub_f32_e32 v83, 1.0, v83
	v_mul_f32_e32 v57, 0x3fb8aa3b, v57
	v_mul_f32_e32 v56, 0x3fb8aa3b, v56
	v_sub_f32_e32 v53, v53, v61
	v_mul_f32_e32 v75, v83, v75
	v_rcp_f32_e32 v83, v58
	v_exp_f32_e32 v57, v57
	v_exp_f32_e32 v56, v56
	v_med3_f32 v53, v53, s76, v113
	v_sub_f32_e32 v55, v55, v63
	v_mul_f32_e32 v53, 0x3fb8aa3b, v53
	v_med3_f32 v55, v55, s76, v113
	v_exp_f32_e32 v53, v53
	v_sub_f32_e32 v82, 1.0, v82
	v_sub_f32_e32 v70, v74, v70
	v_and_b32_e32 v74, 0xffff0000, v10
	v_mul_f32_e32 v55, 0x3fb8aa3b, v55
	v_sub_f32_e32 v54, v54, v62
	v_sub_f32_e32 v52, v52, v60
	v_mul_f32_e32 v82, v82, v83
	v_rcp_f32_e32 v83, v57
	v_mul_f32_e32 v57, v57, v74
	v_rcp_f32_e32 v74, v56
	v_exp_f32_e32 v55, v55
	v_med3_f32 v54, v54, s76, v113
	v_med3_f32 v52, v52, s76, v113
	v_mul_f32_e32 v54, 0x3fb8aa3b, v54
	v_sub_f32_e32 v62, v66, v62
	v_and_b32_e32 v66, 0xffff0000, v8
	v_mul_f32_e32 v52, 0x3fb8aa3b, v52
	v_exp_f32_e32 v54, v54
	v_mul_f32_e32 v66, v53, v66
	v_rcp_f32_e32 v53, v53
	v_exp_f32_e32 v52, v52
	v_sub_f32_e32 v80, 1.0, v80
	v_mul_f32_e32 v74, v80, v74
	v_rcp_f32_e32 v80, v55
	v_sub_f32_e32 v68, v72, v68
	v_and_b32_e32 v72, 0xffff0000, v9
	v_sub_f32_e32 v77, 1.0, v77
	v_sub_f32_e32 v60, v64, v60
	v_mul_f32_e32 v55, v55, v72
	v_rcp_f32_e32 v72, v54
	v_sub_f32_e32 v61, v65, v61
	v_mul_f32_e32 v65, v77, v53
	v_rcp_f32_e32 v77, v52
	v_mul_f32_e32 v60, 0x3fb8aa3b, v60
	v_and_b32_e32 v84, 0xffff0000, v11
	v_sub_f32_e32 v81, 1.0, v81
	v_sub_f32_e32 v79, 1.0, v79
	v_mul_f32_e32 v61, 0x3fb8aa3b, v61
	v_exp_f32_e32 v60, v60
	v_mul_f32_e32 v59, v59, v84
	v_lshlrev_b32_e32 v84, 16, v11
	v_sub_f32_e32 v69, v73, v69
	v_mul_f32_e32 v73, v81, v83
	v_lshlrev_b32_e32 v81, 16, v10
	v_sub_f32_e32 v63, v67, v63
	v_mul_f32_e32 v67, v79, v80
	v_lshlrev_b32_e32 v79, 16, v9
	v_mul_f32_e32 v62, 0x3fb8aa3b, v62
	v_exp_f32_e32 v61, v61
	v_lshlrev_b32_e32 v53, 16, v8
	v_mul_f32_e32 v58, v58, v84
	v_mul_f32_e32 v56, v56, v81
	v_mul_f32_e32 v63, 0x3fb8aa3b, v63
	v_sub_f32_e32 v78, 1.0, v78
	v_mul_f32_e32 v54, v54, v79
	v_exp_f32_e32 v62, v62
	v_sub_f32_e32 v64, 1.0, v76
	v_mul_f32_e32 v52, v52, v53
	v_mul_f32_e32 v68, 0x3fb8aa3b, v68
	v_exp_f32_e32 v63, v63
	v_mul_f32_e32 v72, v78, v72
	v_mul_f32_e32 v64, v64, v77
	v_cvt_pk_bf16_f32 v52, v52, v66
	v_cvt_pk_bf16_f32 v53, v54, v55
	v_cvt_pk_bf16_f32 v54, v56, v57
	v_cvt_pk_bf16_f32 v55, v58, v59
	v_add3_u32 v56, s67, v118, v103
	v_mul_f32_e32 v69, 0x3fb8aa3b, v69
	v_exp_f32_e32 v68, v68
	v_mul_f32_e32 v60, v60, v64
	ds_write_b128 v56, v[52:55]
	v_cvt_pk_bf16_f32 v52, v64, v65
	v_cvt_pk_bf16_f32 v53, v72, v67
	v_cvt_pk_bf16_f32 v54, v74, v73
	v_cvt_pk_bf16_f32 v55, v82, v75
	v_mul_f32_e32 v70, 0x3fb8aa3b, v70
	v_exp_f32_e32 v69, v69
	v_mul_f32_e32 v61, v61, v65
	ds_write_b128 v56, v[52:55] offset:8704
	v_cvt_pk_bf16_f32 v52, v60, s0
	v_add3_u32 v53, s67, v119, v123
	v_mul_f32_e32 v71, 0x3fb8aa3b, v71
	v_exp_f32_e32 v70, v70
	v_mul_f32_e32 v62, v62, v72
	ds_write_b16 v53, v52 offset:17408
	ds_write_b16 v53, v16 offset:27648
	v_cvt_pk_bf16_f32 v52, v61, s0
	v_exp_f32_e32 v71, v71
	v_mul_f32_e32 v63, v63, v67
	ds_write_b16 v53, v52 offset:17488
	ds_write_b16_d16_hi v53, v16 offset:27728
	v_cvt_pk_bf16_f32 v52, v62, s0
	v_mul_f32_e32 v68, v68, v74
	ds_write_b16 v53, v52 offset:17568
	ds_write_b16 v53, v17 offset:27808
	v_cvt_pk_bf16_f32 v52, v63, s0
	v_mul_f32_e32 v69, v69, v73
	ds_write_b16 v53, v52 offset:17648
	ds_write_b16_d16_hi v53, v17 offset:27888
	v_cvt_pk_bf16_f32 v52, v68, s0
	v_mul_f32_e32 v70, v70, v82
	ds_write_b16 v53, v52 offset:17728
	ds_write_b16 v53, v18 offset:27968
	v_cvt_pk_bf16_f32 v52, v69, s0
	v_mul_f32_e32 v71, v71, v75
	ds_write_b16 v53, v52 offset:17808
	ds_write_b16_d16_hi v53, v18 offset:28048
	v_cvt_pk_bf16_f32 v52, v70, s0
	ds_write_b16 v53, v52 offset:17888
	ds_write_b16 v53, v19 offset:28128
	v_cvt_pk_bf16_f32 v52, v71, s0
	s_cmp_eq_u32 s64, 0xfc0000
	ds_write_b16 v53, v52 offset:17968
	ds_write_b16_d16_hi v53, v19 offset:28208
	s_cbranch_scc1 .LBB0_1394
	s_waitcnt vmcnt(8)
	v_mov_b32_e32 v8, v176
	v_mov_b32_e32 v9, v177
	v_mov_b32_e32 v10, v178
	v_mov_b32_e32 v11, v179
	v_mov_b32_e32 v12, v180
	v_mov_b32_e32 v13, v181
	v_mov_b32_e32 v14, v182
	v_mov_b32_e32 v15, v183
	v_mov_b32_e32 v16, v184
	v_mov_b32_e32 v17, v185
	v_mov_b32_e32 v18, v186
	v_mov_b32_e32 v19, v187
.LBB0_1394:
	v_add_u32_e32 v162, s67, v120
	v_add_u32_e32 v152, v162, v121
	v_add_u32_e32 v148, 0x2000, v152
	v_add_u32_e32 v156, 0x1000, v152
	s_cmp_lt_u32 s64, 0xf80000
	s_cbranch_scc0 .Lhg_nopf
	v_lshl_add_u64 v[188:189], v[108:109], 0, s[64:65]
	v_add_co_u32_e32 v190, vcc, 0xc280000, v188
	s_nop 1
	v_addc_co_u32_e32 v191, vcc, 0, v189, vcc
	v_add_co_u32_e32 v188, vcc, 0xc281000, v188
	s_nop 1
	v_addc_co_u32_e32 v189, vcc, 0, v189, vcc
	global_load_dwordx4 v[176:179], v[190:191], off
	global_load_dwordx4 v[180:183], v[190:191], off offset:2048
	global_load_dwordx4 v[184:187], v[188:189], off
; #define LAS __attribute__((address_space(3)))
; __device__ __forceinline__ bf16x8 pack8(const f32x4 a, const f32x4 b) { const u32x4 v = {pk2(a[0], a[1]), pk2(a[2], a[3]), pk2(b[0], b[1]), pk2(b[2], b[3])}; return __builtin_bit_cast(bf16x8, v); }
; __device__ __forceinline__ void hgrn_chunked_bh(const Ctx& F, int b, int h) {
;     ...
;         for (int i = 0; i < 4; ++i) { const bf16_t* gp = proj + ((size_t)b * S + 32 * c + w + 8 * i) * IN_ODD + 3072 + h * 128; gq[i][0] = gp[lane]; gq[i][1] = gp[64 + lane]; }
;         __syncthreads();
;         {
;             bf16x8 qf[4][2];
; #pragma unroll
;             for (int s = 0; s < 4; ++s)
; #pragma unroll
;                 for (int nt = 0; nt < 2; ++nt) qf[s][nt] = ld_frag2(Ls + H_QM + (c16 + 16 * nt) * HQP + (32 * s + 4 * g) * 2);
;             f32x4 at[2][2];
; #pragma unroll
;             for (int mt = 0; mt < 2; ++mt)
; #pragma unroll
;                 for (int nt = 0; nt < 2; ++nt) at[mt][nt] = (f32x4){0.f, 0.f, 0.f, 0.f};
; #pragma unroll
;             for (int s = 0; s < 4; ++s)
; #pragma unroll
;                 for (int mt = 0; mt < 2; ++mt) { const bf16x8 ka = ld_frag2(Ls + H_KM + (c16 + 16 * mt) * HQP + (32 * s + 4 * g) * 2);
; #pragma unroll
;                     for (int nt = 0; nt < 2; ++nt) at[mt][nt] = __builtin_amdgcn_mfma_f32_16x16x32_bf16(ka, qf[s][nt], at[mt][nt], 0, 0, 0); }
; #pragma unroll
;             for (int mt = 0; mt < 2; ++mt)
; #pragma unroll
;                 for (int nt = 0; nt < 2; ++nt)
; #pragma unroll
;                     for (int r = 0; r < 4; ++r) if (16 * mt + 4 * g + r > c16 + 16 * nt) at[mt][nt][r] = 0.f;
;             f32x4 oT[2] = {(f32x4){0.f, 0.f, 0.f, 0.f}, (f32x4){0.f, 0.f, 0.f, 0.f}};
; #pragma unroll
;             for (int s = 0; s < 4; ++s) {
;                 const f32x4 e0 = *(const LAS f32x4*)(Ls + H_EM + (32 * s + 4 * g) * 4), e1 = *(const LAS f32x4*)(Ls + H_EM + (32 * s + 16 + 4 * g) * 4);
;                 const bf16x8 sA = pack8(st[2 * s] * e0, st[2 * s + 1] * e1);
; #pragma unroll
;                 for (int nt = 0; nt < 2; ++nt) oT[nt] = __builtin_amdgcn_mfma_f32_16x16x32_bf16(sA, qf[s][nt], oT[nt], 0, 0, 0);
;             }
.Lhg_nopf:
	s_waitcnt lgkmcnt(0)
	s_barrier
	ds_read2_b64 v[60:63], v148 offset0:64 offset1:68
	ds_read2_b64 v[56:59], v152 offset1:4
	ds_read2_b64 v[52:55], v156 offset0:32 offset1:36
	v_add_u32_e32 v157, 0x3000, v152
	s_waitcnt lgkmcnt(1)
	v_mfma_f32_16x16x32_bf16 v[68:71], v[60:63], v[56:59], 0
	ds_read2_b64 v[80:83], v148 offset0:72 offset1:76
	ds_read2_b64 v[64:67], v152 offset0:8 offset1:12
	ds_read2_b64 v[88:91], v148 offset0:80 offset1:84
	s_waitcnt lgkmcnt(3)
	v_mfma_f32_16x16x32_bf16 v[72:75], v[60:63], v[52:55], 0
	ds_read2_b64 v[60:63], v157 offset0:96 offset1:100
	ds_read2_b64 v[148:151], v148 offset0:88 offset1:92
	v_add_u32_e32 v167, s67, v117
	s_waitcnt lgkmcnt(1)
	v_mfma_f32_16x16x32_bf16 v[76:79], v[60:63], v[56:59], 0
	s_cmp_eq_u32 s64, 0
	v_mfma_f32_16x16x32_bf16 v[84:87], v[60:63], v[52:55], 0
	ds_read2_b64 v[60:63], v156 offset0:40 offset1:44
	v_mfma_f32_16x16x32_bf16 v[68:71], v[80:83], v[64:67], v[68:71]
	s_waitcnt lgkmcnt(0)
	v_mfma_f32_16x16x32_bf16 v[80:83], v[80:83], v[60:63], v[72:75]
	s_nop 2
	ds_read2_b64 v[72:75], v157 offset0:104 offset1:108
	s_waitcnt lgkmcnt(0)
	v_mfma_f32_16x16x32_bf16 v[76:79], v[72:75], v[64:67], v[76:79]
	v_mfma_f32_16x16x32_bf16 v[84:87], v[72:75], v[60:63], v[84:87]
	ds_read2_b64 v[72:75], v152 offset0:16 offset1:20
	s_waitcnt lgkmcnt(0)
	v_mfma_f32_16x16x32_bf16 v[92:95], v[88:91], v[72:75], v[68:71]
	s_nop 2
	ds_read2_b64 v[68:71], v156 offset0:48 offset1:52
	s_waitcnt lgkmcnt(0)
	v_mfma_f32_16x16x32_bf16 v[88:91], v[88:91], v[68:71], v[80:83]
	s_nop 2
	ds_read2_b64 v[80:83], v157 offset0:112 offset1:116
	s_waitcnt lgkmcnt(0)
	v_mfma_f32_16x16x32_bf16 v[96:99], v[80:83], v[72:75], v[76:79]
	s_nop 2
	ds_read2_b64 v[76:79], v152 offset0:24 offset1:28
	v_mfma_f32_16x16x32_bf16 v[84:87], v[80:83], v[68:71], v[84:87]
	ds_read2_b64 v[80:83], v156 offset0:56 offset1:60
	s_waitcnt lgkmcnt(1)
	v_mfma_f32_16x16x32_bf16 v[152:155], v[148:151], v[76:79], v[92:95]
	s_waitcnt lgkmcnt(0)
	v_mfma_f32_16x16x32_bf16 v[92:95], v[148:151], v[80:83], v[88:91]
	ds_read2_b64 v[148:151], v157 offset0:120 offset1:124
	s_nop 4
	v_cndmask_b32_e64 v164, 0, v153, s[10:11]
	v_cndmask_b32_e64 v165, v154, 0, s[16:17]
	s_waitcnt lgkmcnt(0)
	v_mfma_f32_16x16x32_bf16 v[88:91], v[148:151], v[76:79], v[96:99]
	s_nop 2
	v_mov_b32_e32 v96, s51
	v_cndmask_b32_e64 v96, v152, v96, s[8:9]
	v_cndmask_b32_e64 v163, v96, v152, s[10:11]
	v_mov_b32_e32 v96, s51
	v_cndmask_b32_e64 v96, v92, v96, s[12:13]
	v_mfma_f32_16x16x32_bf16 v[84:87], v[148:151], v[80:83], v[84:87]
	ds_read_b128 v[148:151], v167 offset:37888
	v_cndmask_b32_e64 v168, v96, v92, s[14:15]
	v_add_u32_e32 v92, s67, v124
	v_cndmask_b32_e64 v166, v155, 0, s[18:19]
	ds_read_b128 v[96:99], v92 offset:37888
	ds_read_b128 v[152:155], v167 offset:38016
	s_waitcnt lgkmcnt(2)
	v_pk_mul_f32 v[156:157], v[22:23], v[150:151]
	v_pk_mul_f32 v[158:159], v[20:21], v[148:149]
	v_cndmask_b32_e64 v169, 0, v93, s[14:15]
	s_waitcnt lgkmcnt(1)
	v_pk_mul_f32 v[160:161], v[26:27], v[98:99]
	v_pk_mul_f32 v[98:99], v[24:25], v[96:97]
	v_cvt_pk_bf16_f32 v96, v158, v159
	v_cvt_pk_bf16_f32 v97, v156, v157
	v_cvt_pk_bf16_f32 v98, v98, v99
	v_cvt_pk_bf16_f32 v99, v160, v161
	v_cndmask_b32_e64 v170, v94, 0, s[20:21]
	v_cndmask_b32_e64 v171, v95, 0, s[22:23]
	ds_read_b128 v[92:95], v167 offset:38080
	v_mfma_f32_16x16x32_bf16 v[56:59], v[96:99], v[56:59], 0
	s_waitcnt lgkmcnt(1)
	v_pk_mul_f32 v[156:157], v[30:31], v[154:155]
	v_pk_mul_f32 v[158:159], v[28:29], v[152:153]
	ds_read_b128 v[152:155], v167 offset:38144
	s_waitcnt lgkmcnt(1)
	v_pk_mul_f32 v[160:161], v[34:35], v[94:95]
	v_pk_mul_f32 v[94:95], v[32:33], v[92:93]
	v_mfma_f32_16x16x32_bf16 v[52:55], v[96:99], v[52:55], 0
	v_mov_b32_e32 v96, s51
	v_cvt_pk_bf16_f32 v92, v158, v159
	v_cvt_pk_bf16_f32 v93, v156, v157
	v_cvt_pk_bf16_f32 v94, v94, v95
	v_cvt_pk_bf16_f32 v95, v160, v161
	v_cndmask_b32_e64 v158, v88, v96, s[24:25]
	ds_read_b128 v[96:99], v167 offset:38208
	v_mfma_f32_16x16x32_bf16 v[56:59], v[92:95], v[64:67], v[56:59]
	s_waitcnt lgkmcnt(1)
	v_pk_mul_f32 v[154:155], v[38:39], v[154:155]
	v_pk_mul_f32 v[152:153], v[36:37], v[152:153]
	ds_read_b128 v[64:67], v167 offset:38272
	s_waitcnt lgkmcnt(1)
; #define LAS __attribute__((address_space(3)))
; __device__ __forceinline__ bf16x8 pack8(const f32x4 a, const f32x4 b) { const u32x4 v = {pk2(a[0], a[1]), pk2(a[2], a[3]), pk2(b[0], b[1]), pk2(b[2], b[3])}; return __builtin_bit_cast(bf16x8, v); }
; __device__ __forceinline__ void hgrn_chunked_bh(const Ctx& F, int b, int h) {
;     ...
; #pragma unroll
;             for (int s = 0; s < 4; ++s) {
;                 const f32x4 e0 = *(const LAS f32x4*)(Ls + H_EM + (32 * s + 4 * g) * 4), e1 = *(const LAS f32x4*)(Ls + H_EM + (32 * s + 16 + 4 * g) * 4);
;                 const bf16x8 sA = pack8(st[2 * s] * e0, st[2 * s + 1] * e1);
; #pragma unroll
;                 for (int nt = 0; nt < 2; ++nt) oT[nt] = __builtin_amdgcn_mfma_f32_16x16x32_bf16(sA, qf[s][nt], oT[nt], 0, 0, 0);
;             }
;             const bf16x8 vA = ld_frag2(Ls + H_VT + (16 * w + c16) * HTP + 8 * g);
; #pragma unroll
;             for (int nt = 0; nt < 2; ++nt) oT[nt] = __builtin_amdgcn_mfma_f32_16x16x32_bf16(vA, pack8(at[0][nt], at[1][nt]), oT[nt], 0, 0, 0);
; #pragma unroll
;             for (int mt = 0; mt < 8; ++mt) { const f32x4 el = *(const LAS f32x4*)(Ls + H_EL + (16 * mt + 4 * g) * 4);
;                 const bf16x8 kdA = ld_frag2(Ls + H_KD + (16 * mt + c16) * HTP + 8 * g);
;                 st[mt] = __builtin_amdgcn_mfma_f32_16x16x32_bf16(kdA, vA, st[mt] * el, 0, 0, 0); }
; #pragma unroll
;             for (int nt = 0; nt < 2; ++nt) *(LAS f32x4*)(Ls + H_O + (c16 + 16 * nt) * HOP + (16 * w + 4 * g) * 4) = oT[nt];
;         }
;         if (c > 0) hgrn_post(F, L + ((c - 1) & 1) * HSTG, Y, b, h, c - 1, w, lane, gn0, gn1, gqp);
	v_pk_mul_f32 v[156:157], v[42:43], v[98:99]
	v_pk_mul_f32 v[98:99], v[40:41], v[96:97]
	v_cvt_pk_bf16_f32 v96, v152, v153
	v_cvt_pk_bf16_f32 v97, v154, v155
	v_cvt_pk_bf16_f32 v98, v98, v99
	v_cvt_pk_bf16_f32 v99, v156, v157
	v_mfma_f32_16x16x32_bf16 v[52:55], v[92:95], v[60:63], v[52:55]
	ds_read_b128 v[60:63], v167 offset:38336
	v_cndmask_b32_e64 v92, v89, 0, s[26:27]
	v_cndmask_b32_e64 v90, v90, 0, s[28:29]
	v_mfma_f32_16x16x32_bf16 v[52:55], v[96:99], v[68:71], v[52:55]
	v_mov_b32_e32 v68, s51
	v_cndmask_b32_e64 v84, v84, v68, s[8:9]
	v_add_u32_e32 v68, v162, v122
	v_mfma_f32_16x16x32_bf16 v[56:59], v[96:99], v[72:75], v[56:59]
	s_waitcnt lgkmcnt(1)
	v_pk_mul_f32 v[72:73], v[46:47], v[66:67]
	v_pk_mul_f32 v[74:75], v[44:45], v[64:65]
	ds_read_b128 v[64:67], v167 offset:38400
	s_waitcnt lgkmcnt(1)
	v_pk_mul_f32 v[88:89], v[50:51], v[62:63]
	v_pk_mul_f32 v[62:63], v[48:49], v[60:61]
	v_add_u32_e32 v68, 0x6800, v68
	v_cvt_pk_bf16_f32 v60, v74, v75
	v_cvt_pk_bf16_f32 v61, v72, v73
	v_cvt_pk_bf16_f32 v62, v62, v63
	v_cvt_pk_bf16_f32 v63, v88, v89
	ds_read2_b64 v[68:71], v68 offset0:128 offset1:132
	v_cndmask_b32_e64 v72, v91, 0, s[30:31]
	v_mfma_f32_16x16x32_bf16 v[56:59], v[60:63], v[76:79], v[56:59]
	v_cndmask_b32_e64 v76, v85, 0, s[34:35]
	v_cndmask_b32_e64 v77, v86, 0, s[36:37]
	v_cndmask_b32_e64 v78, v87, 0, s[38:39]
	v_mfma_f32_16x16x32_bf16 v[52:55], v[60:63], v[80:83], v[52:55]
	v_cvt_pk_bf16_f32 v60, v163, v164
	v_cvt_pk_bf16_f32 v61, v165, v166
	v_cvt_pk_bf16_f32 v62, v158, v92
	v_cvt_pk_bf16_f32 v63, v90, v72
	v_add_u32_e32 v80, v162, v133
	v_add_u32_e32 v81, 0x4800, v80
	s_waitcnt lgkmcnt(0)
	v_mfma_f32_16x16x32_bf16 v[56:59], v[68:71], v[60:63], v[56:59]
	v_add_u32_e32 v62, 0x4000, v80
	ds_read2_b64 v[72:75], v62 offset0:128 offset1:132
	v_cvt_pk_bf16_f32 v60, v168, v169
	v_cvt_pk_bf16_f32 v61, v170, v171
	v_cvt_pk_bf16_f32 v62, v84, v76
	v_cvt_pk_bf16_f32 v63, v77, v78
	ds_read_b128 v[148:151], v167 offset:38848
	ds_read_b128 v[76:79], v167 offset:38464
	v_mfma_f32_16x16x32_bf16 v[52:55], v[68:71], v[60:63], v[52:55]
	ds_read2_b64 v[60:63], v81 offset0:32 offset1:36
	v_pk_mul_f32 v[20:21], v[20:21], v[64:65]
	v_pk_mul_f32 v[22:23], v[22:23], v[66:67]
	s_waitcnt lgkmcnt(1)
	v_pk_mul_f32 v[24:25], v[24:25], v[76:77]
	v_pk_mul_f32 v[26:27], v[26:27], v[78:79]
	v_mfma_f32_16x16x32_bf16 v[20:23], v[72:75], v[68:71], v[20:23]
	ds_read_b128 v[64:67], v167 offset:38528
	ds_read2_b64 v[72:75], v81 offset0:192 offset1:196
	v_add_u32_e32 v81, 0x5800, v80
	v_pk_mul_f32 v[48:49], v[48:49], v[148:149]
	s_waitcnt lgkmcnt(2)
	v_mfma_f32_16x16x32_bf16 v[24:27], v[60:63], v[68:71], v[24:27]
	v_add_u32_e32 v60, 0x5000, v80
	s_waitcnt lgkmcnt(1)
	v_pk_mul_f32 v[28:29], v[28:29], v[64:65]
	v_pk_mul_f32 v[30:31], v[30:31], v[66:67]
	ds_read2_b64 v[60:63], v60 offset0:96 offset1:100
	ds_read_b128 v[64:67], v167 offset:38592
	s_waitcnt lgkmcnt(2)
	v_mfma_f32_16x16x32_bf16 v[28:31], v[72:75], v[68:71], v[28:31]
	ds_read2_b64 v[72:75], v81 offset1:4
	ds_read_b128 v[76:79], v167 offset:38656
	v_pk_mul_f32 v[50:51], v[50:51], v[150:151]
	s_waitcnt lgkmcnt(2)
	v_pk_mul_f32 v[32:33], v[32:33], v[64:65]
	v_pk_mul_f32 v[34:35], v[34:35], v[66:67]
	ds_read2_b64 v[64:67], v81 offset0:160 offset1:164
	s_waitcnt lgkmcnt(1)
	v_pk_mul_f32 v[36:37], v[36:37], v[76:77]
	v_mfma_f32_16x16x32_bf16 v[32:35], v[60:63], v[68:71], v[32:35]
	ds_read_b128 v[60:63], v167 offset:38720
	v_pk_mul_f32 v[38:39], v[38:39], v[78:79]
	s_nop 1
	v_mfma_f32_16x16x32_bf16 v[36:39], v[72:75], v[68:71], v[36:39]
	ds_read_b128 v[72:75], v167 offset:38784
	s_waitcnt lgkmcnt(1)
	v_pk_mul_f32 v[40:41], v[40:41], v[60:61]
	v_pk_mul_f32 v[42:43], v[42:43], v[62:63]
	s_waitcnt lgkmcnt(0)
	v_pk_mul_f32 v[44:45], v[44:45], v[72:73]
	v_mfma_f32_16x16x32_bf16 v[40:43], v[64:67], v[68:71], v[40:43]
	v_add_u32_e32 v64, 0x6000, v80
	ds_read2_b64 v[60:63], v64 offset0:64 offset1:68
	v_pk_mul_f32 v[46:47], v[46:47], v[74:75]
	s_waitcnt lgkmcnt(0)
	s_nop 0
	v_mfma_f32_16x16x32_bf16 v[44:47], v[60:63], v[68:71], v[44:47]
	ds_read2_b64 v[60:63], v64 offset0:224 offset1:228
	s_waitcnt lgkmcnt(0)
	v_mfma_f32_16x16x32_bf16 v[48:51], v[60:63], v[68:71], v[48:51]
	v_add3_u32 v60, v167, s33, v134
	ds_write_b128 v60, v[56:59] offset:40960
	ds_write_b128 v60, v[52:55] offset:49408
	s_cbranch_scc1 .LBB0_1378
	s_cmp_lt_u32 s64, 0xf80000
	s_cbranch_scc0 .Lhg_w0
	s_waitcnt vmcnt(3)
	s_branch .Lhg_wd

; #define LAS __attribute__((address_space(3)))
; __device__ __forceinline__ float bf2f(bf16_t v) { return __uint_as_float(((unsigned)v) << 16); }
; __device__ __forceinline__ bf16_t f2bf(float f) { return (bf16_t)(pk2(f, 0.f) & 0xffffu); }
; __device__ __forceinline__ float wave_sum_fast(float x) { x = reduce16(x); return (rl_(x, 0) + rl_(x, 16)) + (rl_(x, 32) + rl_(x, 48)); }
; __device__ __forceinline__ void hgrn_post(const Ctx& F, const LAS unsigned char* Lp, bf16_t* Y, int b, int h, int c, int w, int lane, float gn0, float gn1, const bf16_t (&gq)[4][2]) {
; #pragma unroll
;     for (int i = 0; i < 4; ++i) {
;         const int tl = w + 8 * i; const size_t row = (size_t)b * S + 32 * c + tl;
;         const float oa = *(const LAS float*)(Lp + H_O + tl * HOP + 4 * lane), ob = *(const LAS float*)(Lp + H_O + tl * HOP + 4 * (64 + lane));
;         const float rstd = 1.0f / sqrtf(wave_sum_fast(oa * oa + ob * ob) * (1.0f / 128.f) + 1e-6f);
;         Y[row * D + h * 128 + lane] = f2bf(oa * rstd * gn0 * bf2f(gq[i][0]));
;         Y[row * D + h * 128 + 64 + lane] = f2bf(ob * rstd * gn1 * bf2f(gq[i][1]));
;     }
; }
.Lhg_wd:
	v_perm_b32 v139, v147, v146, s78
	v_perm_b32 v138, v144, v143, s78
	v_perm_b32 v137, v140, v145, s78
	v_perm_b32 v136, v142, v141, s78
	s_bitcmp1_b32 s66, 0
	s_cselect_b32 s40, 0xe200, 0
	s_or_b32 s81, s60, s42
	s_add_u32 s66, s81, s50
	s_addc_u32 s67, s61, 0
	s_add_i32 s40, s43, s40
	v_add_u32_e32 v58, s40, v135
	ds_read2st64_b32 v[52:53], v58 offset0:160 offset1:161
	ds_read2st64_b32 v[54:55], v58 offset0:193 offset1:194
	v_and_b32_e32 v63, 0xffff0000, v139
	s_waitcnt lgkmcnt(1)
	v_mul_f32_e32 v56, v53, v53
	v_fmac_f32_e32 v56, v52, v52
	s_nop 1
	v_add_f32_dpp v56, v56, v56 quad_perm:[1,0,3,2] row_mask:0xf bank_mask:0xf bound_ctrl:1
	s_nop 1
	v_add_f32_dpp v56, v56, v56 quad_perm:[2,3,0,1] row_mask:0xf bank_mask:0xf bound_ctrl:1
	s_nop 1
	v_add_f32_dpp v56, v56, v56 row_half_mirror row_mask:0xf bank_mask:0xf bound_ctrl:1
	s_nop 1
	v_add_f32_dpp v56, v56, v56 row_mirror row_mask:0xf bank_mask:0xf bound_ctrl:1
	s_nop 0
	v_readlane_b32 s41, v56, 16
	v_readlane_b32 s40, v56, 0
	s_nop 0
	v_mov_b32_e32 v57, s41
	v_readlane_b32 s41, v56, 48
	v_add_f32_e32 v57, s40, v57
	v_readlane_b32 s40, v56, 32
	v_mov_b32_e32 v56, s41
	s_nop 0
	v_add_f32_e32 v56, s40, v56
	v_add_f32_e32 v56, v57, v56
	v_fmamk_f32 v56, v56, 0x3c000000, v110
	v_rsq_f32_e32 v60, v56
	s_lshl_b64 s[40:41], s[66:67], 11
	v_add_u32_e32 v61, 0x80, v58
	v_mul_f32_e32 v52, v52, v60
	ds_read2st64_b32 v[58:59], v61 offset0:176 offset1:177
	v_mul_f32_e32 v52, v115, v52
	v_lshlrev_b32_e32 v56, 16, v139
	v_mul_f32_e32 v52, v52, v56
	v_cvt_pk_bf16_f32 v52, v52, s0
	v_lshl_add_u64 v[56:57], v[104:105], 0, s[40:41]
	global_store_short v[56:57], v52, off
	v_mul_f32_e32 v52, v53, v60
	v_mul_f32_e32 v60, v114, v52
	ds_read2st64_b32 v[52:53], v61 offset0:209 offset1:210
	s_waitcnt lgkmcnt(1)
	v_mul_f32_e32 v61, v59, v59
	v_fmac_f32_e32 v61, v58, v58
	v_mul_f32_e32 v60, v60, v63
	v_cvt_pk_bf16_f32 v60, v60, s0
	v_add_f32_dpp v61, v61, v61 quad_perm:[1,0,3,2] row_mask:0xf bank_mask:0xf bound_ctrl:1
	global_store_short v[56:57], v60, off offset:128
	s_nop 0
	v_add_f32_dpp v61, v61, v61 quad_perm:[2,3,0,1] row_mask:0xf bank_mask:0xf bound_ctrl:1
	s_nop 1
	v_add_f32_dpp v61, v61, v61 row_half_mirror row_mask:0xf bank_mask:0xf bound_ctrl:1
	s_nop 1
	v_add_f32_dpp v61, v61, v61 row_mirror row_mask:0xf bank_mask:0xf bound_ctrl:1
	s_nop 0
	v_readlane_b32 s41, v61, 16
	v_readlane_b32 s40, v61, 0
	s_nop 0
	v_mov_b32_e32 v62, s41
	v_readlane_b32 s41, v61, 48
	v_add_f32_e32 v62, s40, v62
	v_readlane_b32 s40, v61, 32
	v_mov_b32_e32 v61, s41
	s_nop 0
	v_add_f32_e32 v61, s40, v61
	v_add_f32_e32 v61, v62, v61
	v_fmamk_f32 v61, v61, 0x3c000000, v110
	v_rsq_f32_e32 v60, v61
	s_add_u32 s40, s81, s48
	s_addc_u32 s41, s61, 0
	s_lshl_b64 s[40:41], s[40:41], 11
	v_mul_f32_e32 v56, v58, v60
	v_mul_f32_e32 v56, v115, v56
	v_lshlrev_b32_e32 v57, 16, v138
	v_mul_f32_e32 v56, v56, v57
	v_cvt_pk_bf16_f32 v58, v56, s0
	v_lshl_add_u64 v[56:57], v[104:105], 0, s[40:41]
	global_store_short v[56:57], v58, off
	v_mul_f32_e32 v58, v59, v60
	v_mul_f32_e32 v59, v55, v55
	v_fmac_f32_e32 v59, v54, v54
	v_mul_f32_e32 v58, v114, v58
	v_and_b32_e32 v61, 0xffff0000, v138
	v_add_f32_dpp v59, v59, v59 quad_perm:[1,0,3,2] row_mask:0xf bank_mask:0xf bound_ctrl:1
	v_mul_f32_e32 v58, v58, v61
	v_cvt_pk_bf16_f32 v58, v58, s0
	v_add_f32_dpp v59, v59, v59 quad_perm:[2,3,0,1] row_mask:0xf bank_mask:0xf bound_ctrl:1
	global_store_short v[56:57], v58, off offset:128
	s_nop 0
	v_add_f32_dpp v59, v59, v59 row_half_mirror row_mask:0xf bank_mask:0xf bound_ctrl:1
	s_nop 1
	v_add_f32_dpp v59, v59, v59 row_mirror row_mask:0xf bank_mask:0xf bound_ctrl:1
	s_nop 0
	v_readlane_b32 s41, v59, 16
	v_readlane_b32 s40, v59, 0
	s_nop 0
	v_mov_b32_e32 v60, s41
	v_readlane_b32 s41, v59, 48
	v_add_f32_e32 v60, s40, v60
	v_readlane_b32 s40, v59, 32
	v_mov_b32_e32 v59, s41
	s_nop 0
	v_add_f32_e32 v59, s40, v59
	v_add_f32_e32 v59, v60, v59
	v_fmamk_f32 v59, v59, 0x3c000000, v110
	v_rsq_f32_e32 v58, v59
	s_add_u32 s40, s81, s49
	s_addc_u32 s41, s61, 0
	s_lshl_b64 s[40:41], s[40:41], 11
	v_mul_f32_e32 v54, v54, v58
	v_mul_f32_e32 v54, v115, v54
	v_lshlrev_b32_e32 v56, 16, v137
	v_mul_f32_e32 v54, v54, v56
	v_cvt_pk_bf16_f32 v54, v54, s0
	v_lshl_add_u64 v[56:57], v[104:105], 0, s[40:41]
	global_store_short v[56:57], v54, off
	v_mul_f32_e32 v54, v55, v58
	s_waitcnt lgkmcnt(0)
	v_mul_f32_e32 v55, v53, v53
	v_fmac_f32_e32 v55, v52, v52
	v_mul_f32_e32 v54, v114, v54
	v_and_b32_e32 v59, 0xffff0000, v137
	v_add_f32_dpp v55, v55, v55 quad_perm:[1,0,3,2] row_mask:0xf bank_mask:0xf bound_ctrl:1
	v_mul_f32_e32 v54, v54, v59
	v_cvt_pk_bf16_f32 v54, v54, s0
	v_add_f32_dpp v55, v55, v55 quad_perm:[2,3,0,1] row_mask:0xf bank_mask:0xf bound_ctrl:1
	global_store_short v[56:57], v54, off offset:128
	s_nop 0
	v_add_f32_dpp v55, v55, v55 row_half_mirror row_mask:0xf bank_mask:0xf bound_ctrl:1
	s_nop 1
	v_add_f32_dpp v55, v55, v55 row_mirror row_mask:0xf bank_mask:0xf bound_ctrl:1
	s_nop 0
	v_readlane_b32 s41, v55, 16
	v_readlane_b32 s40, v55, 0
	s_nop 0
	v_mov_b32_e32 v58, s41
	v_readlane_b32 s41, v55, 48
	v_add_f32_e32 v58, s40, v58
	v_readlane_b32 s40, v55, 32
	v_mov_b32_e32 v55, s41
	s_nop 0
	v_add_f32_e32 v55, s40, v55
	v_add_f32_e32 v55, v58, v55
	v_fmamk_f32 v55, v55, 0x3c000000, v110
	v_rsq_f32_e32 v56, v55
	s_add_u32 s40, s81, s54
	s_addc_u32 s41, s61, 0
	s_lshl_b64 s[40:41], s[40:41], 11
	v_mul_f32_e32 v52, v52, v56
	v_mul_f32_e32 v52, v115, v52
	v_lshlrev_b32_e32 v54, 16, v136
	v_mul_f32_e32 v52, v52, v54
	v_cvt_pk_bf16_f32 v52, v52, s0
	v_lshl_add_u64 v[54:55], v[104:105], 0, s[40:41]
	global_store_short v[54:55], v52, off
	v_mul_f32_e32 v52, v53, v56
	v_mul_f32_e32 v52, v114, v52
	v_and_b32_e32 v53, 0xffff0000, v136
	v_mul_f32_e32 v52, v52, v53
	v_cvt_pk_bf16_f32 v52, v52, s0
	global_store_short v[54:55], v52, off offset:128
	s_branch .LBB0_1378
